# hand-scheduled software-pipelined differential-attention tile loop (fragments prefetched 8 MFMAs ahead)
# speedup vs baseline: 1.0157x; 1.0157x over previous
.LBB0_655:
	s_waitcnt vmcnt(0)
	v_mov_b32_e32 v235, 0
	s_bitcmp1_b32 s72, 0
	s_cselect_b32 s46, 0x12800, 0
	s_xor_b32 s12, s46, 0x12800
	v_add_u32_e32 v230, s46, v181
	ds_read_b128 v[194:197], v230 offset:0
	ds_read_b128 v[198:201], v230 offset:32
	ds_read_b128 v[202:205], v230 offset:64
	ds_read_b128 v[206:209], v230 offset:96
	ds_read_b128 v[210:213], v230 offset:8704
	ds_read_b128 v[214:217], v230 offset:8736
	ds_read_b128 v[218:221], v230 offset:8768
	ds_read_b128 v[226:229], v230 offset:8800
	v_add_u32_e32 v231, s46, v185
	v_add_u32_e32 v232, 0x8800, v231
	v_add_u32_e32 v233, s12, v186
	v_add_u32_e32 v234, s12, v1
	s_add_u32 s98, s44, s58
	s_addc_u32 s99, s45, 0
	v_lshl_add_u64 v[236:237], v[192:193], 0, s[98:99]
	global_load_dwordx4 v[162:165], v[236:237], off
	s_add_u32 s98, s44, s59
	s_addc_u32 s99, s45, 0
	v_lshl_add_u64 v[236:237], v[192:193], 0, s[98:99]
	global_load_dwordx4 v[166:169], v[236:237], off
	s_add_u32 s98, s44, s61
	s_addc_u32 s99, s45, 0
	v_lshl_add_u64 v[236:237], v[192:193], 0, s[98:99]
	global_load_dwordx4 v[170:173], v[236:237], off
	s_add_u32 s98, s44, s68
	s_addc_u32 s99, s45, 0
	v_lshl_add_u64 v[236:237], v[192:193], 0, s[98:99]
	global_load_dwordx4 v[174:177], v[236:237], off
	s_branch .Ldf_qk
.Ldf_loop:
	s_bitcmp1_b32 s72, 0
	s_cselect_b32 s46, 0x12800, 0
	s_xor_b32 s12, s46, 0x12800
	v_add_u32_e32 v230, s46, v181
	ds_read_b128 v[194:197], v230 offset:0
	ds_read_b128 v[198:201], v230 offset:32
	ds_read_b128 v[202:205], v230 offset:64
	ds_read_b128 v[206:209], v230 offset:96
	v_mfma_f32_32x32x16_bf16 v[50:65], v[210:213], v[134:137], v[50:65]
	ds_read_b128 v[210:213], v230 offset:8704
	v_add_u32_e32 v231, s46, v185
	v_add_u32_e32 v232, 0x8800, v231
	v_add_u32_e32 v233, s12, v186
	v_add_u32_e32 v234, s12, v1
	v_mfma_f32_32x32x16_bf16 v[66:81], v[214:217], v[134:137], v[66:81]
	ds_read_b128 v[214:217], v230 offset:8736
	v_mfma_f32_32x32x16_bf16 v[34:49], v[218:221], v[134:137], v[34:49]
	ds_read_b128 v[218:221], v230 offset:8768
	v_mfma_f32_32x32x16_bf16 v[18:33], v[226:229], v[134:137], v[18:33]
	ds_read_b128 v[226:229], v230 offset:8800
	s_add_u32 s98, s44, s58
	s_addc_u32 s99, s45, 0
	v_lshl_add_u64 v[236:237], v[192:193], 0, s[98:99]
	global_load_dwordx4 v[162:165], v[236:237], off
	s_add_u32 s98, s44, s59
	s_addc_u32 s99, s45, 0
	v_lshl_add_u64 v[236:237], v[192:193], 0, s[98:99]
	global_load_dwordx4 v[166:169], v[236:237], off
	s_add_u32 s98, s44, s61
	s_addc_u32 s99, s45, 0
	v_lshl_add_u64 v[236:237], v[192:193], 0, s[98:99]
	global_load_dwordx4 v[170:173], v[236:237], off
	s_add_u32 s98, s44, s68
	s_addc_u32 s99, s45, 0
	v_lshl_add_u64 v[236:237], v[192:193], 0, s[98:99]
	global_load_dwordx4 v[174:177], v[236:237], off
.Ldf_qk:
	s_waitcnt lgkmcnt(7)
	v_mfma_f32_32x32x16_bf16 v[82:97], v[194:197], v[158:161], v[2:17]
	s_waitcnt lgkmcnt(6)
	ds_read_b128 v[194:197], v230 offset:17408
	v_mfma_f32_32x32x16_bf16 v[82:97], v[198:201], v[154:157], v[82:97]
	s_waitcnt lgkmcnt(6)
	ds_read_b128 v[198:201], v230 offset:17440
	v_mfma_f32_32x32x16_bf16 v[82:97], v[202:205], v[150:153], v[82:97]
	s_waitcnt lgkmcnt(6)
	ds_read_b128 v[202:205], v230 offset:17472
	v_mfma_f32_32x32x16_bf16 v[82:97], v[206:209], v[146:149], v[82:97]
	s_waitcnt lgkmcnt(6)
	ds_read_b128 v[206:209], v230 offset:17504
	v_mfma_f32_32x32x16_bf16 v[98:113], v[210:213], v[158:161], v[2:17]
	s_waitcnt lgkmcnt(6)
	ds_read_b128 v[210:213], v230 offset:26112
	v_mfma_f32_32x32x16_bf16 v[98:113], v[214:217], v[154:157], v[98:113]
	s_waitcnt lgkmcnt(6)
	ds_read_b128 v[214:217], v230 offset:26144
	v_mfma_f32_32x32x16_bf16 v[98:113], v[218:221], v[150:153], v[98:113]
	s_waitcnt lgkmcnt(6)
	ds_read_b128 v[218:221], v230 offset:26176
	v_mfma_f32_32x32x16_bf16 v[98:113], v[226:229], v[146:149], v[98:113]
	s_waitcnt lgkmcnt(6)
	ds_read_b128 v[226:229], v230 offset:26208
	v_mfma_f32_32x32x16_bf16 v[114:129], v[194:197], v[158:161], v[2:17]
	s_waitcnt lgkmcnt(6)
	ds_read_b64_tr_b16 v[194:195], v231 offset:34816
	ds_read_b64_tr_b16 v[196:197], v231 offset:37376
	v_exp_f32_e32 v82, v82
	v_exp_f32_e32 v83, v83
	v_add_f32_e32 v191, v191, v82
	v_add_f32_e32 v235, v235, v83
	v_cvt_pk_bf16_f32 v82, v82, v83
	v_mfma_f32_32x32x16_bf16 v[114:129], v[198:201], v[154:157], v[114:129]
	s_waitcnt lgkmcnt(7)
	ds_read_b64_tr_b16 v[198:199], v231 offset:34880
	ds_read_b64_tr_b16 v[200:201], v231 offset:37440
	v_exp_f32_e32 v84, v84
	v_exp_f32_e32 v85, v85
	v_add_f32_e32 v191, v191, v84
	v_add_f32_e32 v235, v235, v85
	v_cvt_pk_bf16_f32 v83, v84, v85
	v_mfma_f32_32x32x16_bf16 v[114:129], v[202:205], v[150:153], v[114:129]
	s_waitcnt lgkmcnt(8)
	ds_read_b64_tr_b16 v[202:203], v231 offset:34944
	ds_read_b64_tr_b16 v[204:205], v231 offset:37504
	v_exp_f32_e32 v86, v86
	v_exp_f32_e32 v87, v87
	v_add_f32_e32 v191, v191, v86
	v_add_f32_e32 v235, v235, v87
	v_cvt_pk_bf16_f32 v84, v86, v87
	v_mfma_f32_32x32x16_bf16 v[114:129], v[206:209], v[146:149], v[114:129]
	s_waitcnt lgkmcnt(9)
	ds_read_b64_tr_b16 v[206:207], v231 offset:35008
	ds_read_b64_tr_b16 v[208:209], v231 offset:37568
	v_exp_f32_e32 v88, v88
	v_exp_f32_e32 v89, v89
	v_add_f32_e32 v191, v191, v88
	v_add_f32_e32 v235, v235, v89
	v_cvt_pk_bf16_f32 v85, v88, v89
	v_mfma_f32_32x32x16_bf16 v[130:145], v[210:213], v[158:161], v[2:17]
	s_waitcnt lgkmcnt(10)
	ds_read_b64_tr_b16 v[210:211], v231 offset:39936
	ds_read_b64_tr_b16 v[212:213], v231 offset:42496
	v_exp_f32_e32 v90, v90
	v_exp_f32_e32 v91, v91
	v_add_f32_e32 v191, v191, v90
	v_add_f32_e32 v235, v235, v91
	v_cvt_pk_bf16_f32 v86, v90, v91
	v_mfma_f32_32x32x16_bf16 v[130:145], v[214:217], v[154:157], v[130:145]
	s_waitcnt lgkmcnt(11)
	ds_read_b64_tr_b16 v[214:215], v231 offset:40000
	ds_read_b64_tr_b16 v[216:217], v231 offset:42560
	v_exp_f32_e32 v92, v92
	v_exp_f32_e32 v93, v93
	v_add_f32_e32 v191, v191, v92
	v_add_f32_e32 v235, v235, v93
	v_cvt_pk_bf16_f32 v87, v92, v93
	v_mfma_f32_32x32x16_bf16 v[130:145], v[218:221], v[150:153], v[130:145]
	s_waitcnt lgkmcnt(12)
	ds_read_b64_tr_b16 v[218:219], v231 offset:40064
	ds_read_b64_tr_b16 v[220:221], v231 offset:42624
	v_exp_f32_e32 v94, v94
	v_exp_f32_e32 v95, v95
	v_add_f32_e32 v191, v191, v94
	v_add_f32_e32 v235, v235, v95
	v_cvt_pk_bf16_f32 v88, v94, v95
	v_mfma_f32_32x32x16_bf16 v[130:145], v[226:229], v[146:149], v[130:145]
	s_waitcnt lgkmcnt(12)
	ds_read_b64_tr_b16 v[226:227], v231 offset:40128
	ds_read_b64_tr_b16 v[228:229], v231 offset:42688
	v_exp_f32_e32 v96, v96
	v_exp_f32_e32 v97, v97
	v_add_f32_e32 v191, v191, v96
	v_add_f32_e32 v235, v235, v97
	v_cvt_pk_bf16_f32 v89, v96, v97
	v_mfma_f32_32x32x16_bf16 v[50:65], v[194:197], v[82:85], v[50:65]
	s_waitcnt lgkmcnt(12)
	ds_read_b64_tr_b16 v[194:195], v231 offset:45056
	ds_read_b64_tr_b16 v[196:197], v231 offset:47616
	v_exp_f32_e32 v98, v98
	v_exp_f32_e32 v99, v99
	s_waitcnt vmcnt(3)
	ds_write_b128 v233, v[162:165] offset:0
	v_add_f32_e32 v191, v191, v98
	v_add_f32_e32 v235, v235, v99
	v_cvt_pk_bf16_f32 v98, v98, v99
	v_mfma_f32_32x32x16_bf16 v[66:81], v[198:201], v[82:85], v[66:81]
	s_waitcnt lgkmcnt(13)
	ds_read_b64_tr_b16 v[198:199], v231 offset:45120
	ds_read_b64_tr_b16 v[200:201], v231 offset:47680
	v_exp_f32_e32 v100, v100
	v_exp_f32_e32 v101, v101
	s_waitcnt vmcnt(2)
	s_waitcnt lgkmcnt(14)
	ds_write_b128 v233, v[166:169] offset:8704
	v_add_f32_e32 v191, v191, v100
	v_add_f32_e32 v235, v235, v101
	v_cvt_pk_bf16_f32 v99, v100, v101
	v_mfma_f32_32x32x16_bf16 v[34:49], v[202:205], v[82:85], v[34:49]
	s_waitcnt lgkmcnt(14)
	ds_read_b64_tr_b16 v[202:203], v231 offset:45184
	s_waitcnt lgkmcnt(14)
	ds_read_b64_tr_b16 v[204:205], v231 offset:47744
	v_exp_f32_e32 v102, v102
	v_exp_f32_e32 v103, v103
	s_waitcnt vmcnt(1)
	s_waitcnt lgkmcnt(14)
	ds_write_b128 v233, v[170:173] offset:17408
	v_add_f32_e32 v191, v191, v102
	v_add_f32_e32 v235, v235, v103
	v_cvt_pk_bf16_f32 v100, v102, v103
	v_mfma_f32_32x32x16_bf16 v[18:33], v[206:209], v[82:85], v[18:33]
	s_waitcnt lgkmcnt(14)
	ds_read_b64_tr_b16 v[206:207], v231 offset:45248
	s_waitcnt lgkmcnt(14)
	ds_read_b64_tr_b16 v[208:209], v231 offset:47808
	v_exp_f32_e32 v104, v104
	v_exp_f32_e32 v105, v105
	s_waitcnt vmcnt(0)
	s_waitcnt lgkmcnt(14)
	ds_write_b128 v233, v[174:177] offset:26112
	v_add_f32_e32 v191, v191, v104
	v_add_f32_e32 v235, v235, v105
	v_cvt_pk_bf16_f32 v101, v104, v105
	v_mfma_f32_32x32x16_bf16 v[50:65], v[210:213], v[86:89], v[50:65]
	s_waitcnt lgkmcnt(14)
	ds_read_b64_tr_b16 v[210:211], v231 offset:50176
	s_waitcnt lgkmcnt(14)
	ds_read_b64_tr_b16 v[212:213], v231 offset:52736
	v_exp_f32_e32 v106, v106
	v_exp_f32_e32 v107, v107
	s_add_u32 s98, s44, s58
	s_addc_u32 s99, s45, 0
	v_lshl_add_u64 v[236:237], v[192:193], 0, s[98:99]
	global_load_dwordx4 v[162:165], v[236:237], off offset:2048
	v_add_f32_e32 v191, v191, v106
	v_add_f32_e32 v235, v235, v107
	v_cvt_pk_bf16_f32 v102, v106, v107
	v_mfma_f32_32x32x16_bf16 v[66:81], v[214:217], v[86:89], v[66:81]
	s_waitcnt lgkmcnt(14)
	ds_read_b64_tr_b16 v[214:215], v231 offset:50240
	s_waitcnt lgkmcnt(14)
	ds_read_b64_tr_b16 v[216:217], v231 offset:52800
	v_exp_f32_e32 v108, v108
	v_exp_f32_e32 v109, v109
	s_add_u32 s98, s44, s59
	s_addc_u32 s99, s45, 0
	v_lshl_add_u64 v[236:237], v[192:193], 0, s[98:99]
	global_load_dwordx4 v[166:169], v[236:237], off offset:2048
	v_add_f32_e32 v191, v191, v108
	v_add_f32_e32 v235, v235, v109
	v_cvt_pk_bf16_f32 v103, v108, v109
	v_mfma_f32_32x32x16_bf16 v[34:49], v[218:221], v[86:89], v[34:49]
	s_waitcnt lgkmcnt(14)
	ds_read_b64_tr_b16 v[218:219], v231 offset:50304
	s_waitcnt lgkmcnt(14)
	ds_read_b64_tr_b16 v[220:221], v231 offset:52864
	v_exp_f32_e32 v110, v110
	v_exp_f32_e32 v111, v111
	s_add_u32 s98, s44, s61
	s_addc_u32 s99, s45, 0
	v_lshl_add_u64 v[236:237], v[192:193], 0, s[98:99]
	global_load_dwordx4 v[170:173], v[236:237], off offset:2048
	v_add_f32_e32 v191, v191, v110
	v_add_f32_e32 v235, v235, v111
	v_cvt_pk_bf16_f32 v104, v110, v111
	v_mfma_f32_32x32x16_bf16 v[18:33], v[226:229], v[86:89], v[18:33]
	s_waitcnt lgkmcnt(14)
	ds_read_b64_tr_b16 v[226:227], v231 offset:50368
	s_waitcnt lgkmcnt(14)
	ds_read_b64_tr_b16 v[228:229], v231 offset:52928
	v_exp_f32_e32 v112, v112
	v_exp_f32_e32 v113, v113
	s_add_u32 s98, s44, s68
	s_addc_u32 s99, s45, 0
	v_lshl_add_u64 v[236:237], v[192:193], 0, s[98:99]
	global_load_dwordx4 v[174:177], v[236:237], off offset:2048
	v_add_f32_e32 v191, v191, v112
	v_add_f32_e32 v235, v235, v113
	v_cvt_pk_bf16_f32 v105, v112, v113
	v_mfma_f32_32x32x16_bf16 v[50:65], v[194:197], v[98:101], v[50:65]
	s_waitcnt lgkmcnt(14)
	ds_read_b64_tr_b16 v[194:195], v232 offset:20480
	s_waitcnt lgkmcnt(14)
	ds_read_b64_tr_b16 v[196:197], v232 offset:23040
	v_exp_f32_e32 v114, v114
	v_exp_f32_e32 v115, v115
	v_add_f32_e32 v191, v191, v114
	v_add_f32_e32 v235, v235, v115
	v_cvt_pk_bf16_f32 v114, v114, v115
	v_mfma_f32_32x32x16_bf16 v[66:81], v[198:201], v[98:101], v[66:81]
	s_waitcnt lgkmcnt(14)
	ds_read_b64_tr_b16 v[198:199], v232 offset:20544
	s_waitcnt lgkmcnt(14)
	ds_read_b64_tr_b16 v[200:201], v232 offset:23104
	v_exp_f32_e32 v116, v116
	v_exp_f32_e32 v117, v117
	v_add_f32_e32 v191, v191, v116
	v_add_f32_e32 v235, v235, v117
	v_cvt_pk_bf16_f32 v115, v116, v117
	v_mfma_f32_32x32x16_bf16 v[34:49], v[202:205], v[98:101], v[34:49]
	s_waitcnt lgkmcnt(13)
	ds_read_b64_tr_b16 v[202:203], v232 offset:20608
	ds_read_b64_tr_b16 v[204:205], v232 offset:23168
	v_exp_f32_e32 v118, v118
	v_exp_f32_e32 v119, v119
	v_add_f32_e32 v191, v191, v118
	v_add_f32_e32 v235, v235, v119
	v_cvt_pk_bf16_f32 v116, v118, v119
	v_mfma_f32_32x32x16_bf16 v[18:33], v[206:209], v[98:101], v[18:33]
	s_waitcnt lgkmcnt(12)
	ds_read_b64_tr_b16 v[206:207], v232 offset:20672
	ds_read_b64_tr_b16 v[208:209], v232 offset:23232
	v_exp_f32_e32 v120, v120
	v_exp_f32_e32 v121, v121
	v_add_f32_e32 v191, v191, v120
	v_add_f32_e32 v235, v235, v121
	v_cvt_pk_bf16_f32 v117, v120, v121
	v_mfma_f32_32x32x16_bf16 v[50:65], v[210:213], v[102:105], v[50:65]
	s_waitcnt lgkmcnt(12)
	ds_read_b64_tr_b16 v[210:211], v232 offset:25600
	ds_read_b64_tr_b16 v[212:213], v232 offset:28160
	v_exp_f32_e32 v122, v122
	v_exp_f32_e32 v123, v123
	v_add_f32_e32 v191, v191, v122
	v_add_f32_e32 v235, v235, v123
	v_cvt_pk_bf16_f32 v118, v122, v123
	v_mfma_f32_32x32x16_bf16 v[66:81], v[214:217], v[102:105], v[66:81]
	s_waitcnt lgkmcnt(12)
	ds_read_b64_tr_b16 v[214:215], v232 offset:25664
	ds_read_b64_tr_b16 v[216:217], v232 offset:28224
	v_exp_f32_e32 v124, v124
	v_exp_f32_e32 v125, v125
	v_add_f32_e32 v191, v191, v124
	v_add_f32_e32 v235, v235, v125
	v_cvt_pk_bf16_f32 v119, v124, v125
	v_mfma_f32_32x32x16_bf16 v[34:49], v[218:221], v[102:105], v[34:49]
	s_waitcnt lgkmcnt(12)
	ds_read_b64_tr_b16 v[218:219], v232 offset:25728
	ds_read_b64_tr_b16 v[220:221], v232 offset:28288
	v_exp_f32_e32 v126, v126
	v_exp_f32_e32 v127, v127
	v_add_f32_e32 v191, v191, v126
	v_add_f32_e32 v235, v235, v127
	v_cvt_pk_bf16_f32 v120, v126, v127
	v_mfma_f32_32x32x16_bf16 v[18:33], v[226:229], v[102:105], v[18:33]
	s_waitcnt lgkmcnt(12)
	ds_read_b64_tr_b16 v[226:227], v232 offset:25792
	ds_read_b64_tr_b16 v[228:229], v232 offset:28352
	v_exp_f32_e32 v128, v128
	v_exp_f32_e32 v129, v129
	v_add_f32_e32 v191, v191, v128
	v_add_f32_e32 v235, v235, v129
	v_cvt_pk_bf16_f32 v121, v128, v129
	v_mfma_f32_32x32x16_bf16 v[50:65], v[194:197], v[114:117], v[50:65]
	s_waitcnt lgkmcnt(12)
	ds_read_b64_tr_b16 v[194:195], v232 offset:30720
	ds_read_b64_tr_b16 v[196:197], v232 offset:33280
	v_exp_f32_e32 v130, v130
	v_exp_f32_e32 v131, v131
	v_add_f32_e32 v191, v191, v130
	v_add_f32_e32 v235, v235, v131
	v_cvt_pk_bf16_f32 v130, v130, v131
	v_mfma_f32_32x32x16_bf16 v[66:81], v[198:201], v[114:117], v[66:81]
	s_waitcnt lgkmcnt(12)
	ds_read_b64_tr_b16 v[198:199], v232 offset:30784
	ds_read_b64_tr_b16 v[200:201], v232 offset:33344
	v_exp_f32_e32 v132, v132
	v_exp_f32_e32 v133, v133
	v_add_f32_e32 v191, v191, v132
	v_add_f32_e32 v235, v235, v133
	v_cvt_pk_bf16_f32 v131, v132, v133
	v_mfma_f32_32x32x16_bf16 v[34:49], v[202:205], v[114:117], v[34:49]
	s_waitcnt lgkmcnt(12)
	ds_read_b64_tr_b16 v[202:203], v232 offset:30848
	ds_read_b64_tr_b16 v[204:205], v232 offset:33408
	v_exp_f32_e32 v134, v134
	v_exp_f32_e32 v135, v135
	v_add_f32_e32 v191, v191, v134
	v_add_f32_e32 v235, v235, v135
	v_cvt_pk_bf16_f32 v132, v134, v135
	v_mfma_f32_32x32x16_bf16 v[18:33], v[206:209], v[114:117], v[18:33]
	s_waitcnt lgkmcnt(12)
	ds_read_b64_tr_b16 v[206:207], v232 offset:30912
	ds_read_b64_tr_b16 v[208:209], v232 offset:33472
	v_exp_f32_e32 v136, v136
	v_exp_f32_e32 v137, v137
	v_add_f32_e32 v191, v191, v136
	v_add_f32_e32 v235, v235, v137
	v_cvt_pk_bf16_f32 v133, v136, v137
	v_mfma_f32_32x32x16_bf16 v[50:65], v[210:213], v[118:121], v[50:65]
	s_waitcnt lgkmcnt(12)
	ds_read_b64_tr_b16 v[210:211], v232 offset:35840
	ds_read_b64_tr_b16 v[212:213], v232 offset:38400
	v_exp_f32_e32 v138, v138
	v_exp_f32_e32 v139, v139
	s_waitcnt vmcnt(3)
	ds_write_b128 v234, v[162:165] offset:0
	v_add_f32_e32 v191, v191, v138
	v_add_f32_e32 v235, v235, v139
	v_cvt_pk_bf16_f32 v134, v138, v139
	v_mfma_f32_32x32x16_bf16 v[66:81], v[214:217], v[118:121], v[66:81]
	s_waitcnt lgkmcnt(13)
	ds_read_b64_tr_b16 v[214:215], v232 offset:35904
	ds_read_b64_tr_b16 v[216:217], v232 offset:38464
	v_exp_f32_e32 v140, v140
	v_exp_f32_e32 v141, v141
	s_waitcnt vmcnt(2)
	s_waitcnt lgkmcnt(14)
	ds_write_b128 v234, v[166:169] offset:10240
	v_add_f32_e32 v191, v191, v140
	v_add_f32_e32 v235, v235, v141
	v_cvt_pk_bf16_f32 v135, v140, v141
	v_mfma_f32_32x32x16_bf16 v[34:49], v[218:221], v[118:121], v[34:49]
	s_waitcnt lgkmcnt(14)
	ds_read_b64_tr_b16 v[218:219], v232 offset:35968
	s_waitcnt lgkmcnt(14)
	ds_read_b64_tr_b16 v[220:221], v232 offset:38528
	v_exp_f32_e32 v142, v142
	v_exp_f32_e32 v143, v143
	s_waitcnt vmcnt(1)
	s_waitcnt lgkmcnt(14)
	ds_write_b128 v234, v[170:173] offset:20480
	v_add_f32_e32 v191, v191, v142
	v_add_f32_e32 v235, v235, v143
	v_cvt_pk_bf16_f32 v136, v142, v143
	v_mfma_f32_32x32x16_bf16 v[18:33], v[226:229], v[118:121], v[18:33]
	s_waitcnt lgkmcnt(14)
	ds_read_b64_tr_b16 v[226:227], v232 offset:36032
	s_waitcnt lgkmcnt(14)
	ds_read_b64_tr_b16 v[228:229], v232 offset:38592
	v_exp_f32_e32 v144, v144
	v_exp_f32_e32 v145, v145
	s_waitcnt vmcnt(0)
	s_waitcnt lgkmcnt(14)
	ds_write_b128 v234, v[174:177] offset:30720
	v_add_f32_e32 v191, v191, v144
	v_add_f32_e32 v235, v235, v145
	v_cvt_pk_bf16_f32 v137, v144, v145
	v_mfma_f32_32x32x16_bf16 v[50:65], v[194:197], v[130:133], v[50:65]
	v_mfma_f32_32x32x16_bf16 v[66:81], v[198:201], v[130:133], v[66:81]
	s_waitcnt lgkmcnt(14)
	v_mfma_f32_32x32x16_bf16 v[34:49], v[202:205], v[130:133], v[34:49]
	s_waitcnt lgkmcnt(12)
	v_mfma_f32_32x32x16_bf16 v[18:33], v[206:209], v[130:133], v[18:33]
	s_add_i32 s72, s72, 1
	s_add_u32 s44, s44, 0x180000
	s_addc_u32 s45, s45, 0
	s_cmp_eq_u32 s44, 0x2e80000
	s_waitcnt lgkmcnt(0)
	s_barrier
	s_cbranch_scc0 .Ldf_loop
	v_mfma_f32_32x32x16_bf16 v[50:65], v[210:213], v[134:137], v[50:65]
	v_mfma_f32_32x32x16_bf16 v[66:81], v[214:217], v[134:137], v[66:81]
	v_mfma_f32_32x32x16_bf16 v[34:49], v[218:221], v[134:137], v[34:49]
	v_mfma_f32_32x32x16_bf16 v[18:33], v[226:229], v[134:137], v[18:33]
	v_add_f32_e32 v191, v191, v235
	v_add_u32_e32 v82, 0x12800, v181
	ds_read_b128 v[82:85], v82
	v_add_u32_e32 v90, 0x12820, v181
	v_add_u32_e32 v94, 0x12840, v181
	v_add_u32_e32 v86, 0x14a00, v181
	ds_read_b128 v[86:89], v86
	v_add_u32_e32 v98, 0x12860, v181
	s_waitcnt lgkmcnt(1)
	v_mfma_f32_32x32x16_bf16 v[114:129], v[82:85], v[158:161], v[2:17]
	ds_read_b128 v[82:85], v90
	v_add_u32_e32 v90, 0x14a20, v181
	ds_read_b128 v[90:93], v90
	s_waitcnt lgkmcnt(1)
	v_mfma_f32_32x32x16_bf16 v[114:129], v[82:85], v[154:157], v[114:129]
	ds_read_b128 v[82:85], v94
	v_add_u32_e32 v94, 0x14a40, v181
	ds_read_b128 v[94:97], v94
	s_waitcnt lgkmcnt(1)
	v_mfma_f32_32x32x16_bf16 v[114:129], v[82:85], v[150:153], v[114:129]
	ds_read_b128 v[82:85], v98
	v_add_u32_e32 v98, 0x14a60, v181
	ds_read_b128 v[130:133], v98
	v_mfma_f32_32x32x16_bf16 v[98:113], v[86:89], v[158:161], v[2:17]
	v_add_u32_e32 v86, 0x18e00, v181
	ds_read_b128 v[168:171], v86
	v_mfma_f32_32x32x16_bf16 v[98:113], v[90:93], v[154:157], v[98:113]
	s_waitcnt lgkmcnt(3)
	v_mfma_f32_32x32x16_bf16 v[98:113], v[94:97], v[150:153], v[98:113]
	s_waitcnt lgkmcnt(2)
	v_mfma_f32_32x32x16_bf16 v[114:129], v[82:85], v[146:149], v[114:129]
	v_add_u32_e32 v82, 0x16c00, v181
	ds_read_b128 v[82:85], v82
	s_waitcnt lgkmcnt(2)
	v_mfma_f32_32x32x16_bf16 v[98:113], v[130:133], v[146:149], v[98:113]
	s_nop 7
	v_exp_f32_e32 v163, v114
	v_exp_f32_e32 v165, v116
	v_exp_f32_e32 v162, v117
	v_exp_f32_e32 v116, v119
	v_exp_f32_e32 v117, v120
	v_exp_f32_e32 v114, v122
	v_exp_f32_e32 v122, v124
	s_waitcnt lgkmcnt(0)
	v_mfma_f32_32x32x16_bf16 v[130:145], v[82:85], v[158:161], v[2:17]
	v_add_u32_e32 v82, 0x16c20, v181
	ds_read_b128 v[172:175], v82
	v_exp_f32_e32 v166, v98
	v_exp_f32_e32 v98, v121
	v_exp_f32_e32 v119, v126
	v_exp_f32_e32 v120, v127
	v_exp_f32_e32 v121, v128
	v_mfma_f32_32x32x16_bf16 v[82:97], v[168:171], v[158:161], v[2:17]
	v_exp_f32_e32 v168, v99
	v_add_u32_e32 v99, 0x18e20, v181
	ds_read_b128 v[192:195], v99
	v_add_u32_e32 v99, 0x16c40, v181
	v_exp_f32_e32 v124, v129
	ds_read_b128 v[126:129], v99
	v_add_u32_e32 v99, 0x18e40, v181
	s_waitcnt lgkmcnt(2)
	v_mfma_f32_32x32x16_bf16 v[130:145], v[172:175], v[154:157], v[130:145]
	ds_read_b128 v[174:177], v99
	v_add_u32_e32 v99, 0x16c60, v181
	v_exp_f32_e32 v169, v100
	v_exp_f32_e32 v173, v101
	v_exp_f32_e32 v160, v102
	v_exp_f32_e32 v159, v103
	ds_read_b128 v[100:103], v99
	s_waitcnt lgkmcnt(3)
	v_mfma_f32_32x32x16_bf16 v[82:97], v[192:195], v[154:157], v[82:97]
	v_add_u32_e32 v99, 0x18e60, v181
	ds_read_b128 v[196:199], v99
	v_exp_f32_e32 v164, v115
	v_exp_f32_e32 v118, v118
	v_exp_f32_e32 v158, v108
	v_exp_f32_e32 v167, v109
	v_exp_f32_e32 v161, v110
	s_waitcnt lgkmcnt(3)
	v_mfma_f32_32x32x16_bf16 v[130:145], v[126:129], v[150:153], v[130:145]
	v_exp_f32_e32 v126, v113
	v_exp_f32_e32 v129, v107
	v_exp_f32_e32 v115, v123
	v_exp_f32_e32 v123, v125
	v_exp_f32_e32 v170, v104
	v_exp_f32_e32 v171, v105
	v_exp_f32_e32 v172, v106
	s_waitcnt lgkmcnt(2)
	v_mfma_f32_32x32x16_bf16 v[82:97], v[174:177], v[150:153], v[82:97]
	v_exp_f32_e32 v127, v111
	v_exp_f32_e32 v128, v112
	s_waitcnt lgkmcnt(1)
	v_mfma_f32_32x32x16_bf16 v[130:145], v[100:103], v[146:149], v[130:145]
	s_waitcnt lgkmcnt(0)
	v_mfma_f32_32x32x16_bf16 v[82:97], v[196:199], v[146:149], v[82:97]
	s_nop 9
	v_exp_f32_e32 v99, v130
	v_exp_f32_e32 v100, v131
	v_exp_f32_e32 v113, v132
	v_exp_f32_e32 v101, v133
	v_exp_f32_e32 v102, v134
	v_exp_f32_e32 v103, v135
	v_add_u32_e32 v131, 0x1ba00, v185
	v_exp_f32_e32 v130, v82
	v_add_u32_e32 v82, 0x1b000, v185
	ds_read_b64_tr_b16 v[132:133], v82
	ds_read_b64_tr_b16 v[134:135], v131
	v_add_u32_e32 v82, 0x1b040, v185
	v_exp_f32_e32 v107, v140
	v_exp_f32_e32 v108, v141
	v_exp_f32_e32 v109, v142
	v_exp_f32_e32 v110, v143
	v_add_u32_e32 v131, 0x1ba40, v185
	ds_read_b64_tr_b16 v[140:141], v82
	ds_read_b64_tr_b16 v[142:143], v131
	v_exp_f32_e32 v156, v84
	v_add_u32_e32 v82, 0x1b080, v185
	v_add_u32_e32 v84, 0x1ba80, v185
	v_exp_f32_e32 v131, v83
	v_exp_f32_e32 v157, v85
	ds_read_b64_tr_b16 v[82:83], v82
	ds_read_b64_tr_b16 v[84:85], v84
	v_exp_f32_e32 v104, v136
	v_exp_f32_e32 v105, v137
	v_exp_f32_e32 v106, v138
	v_exp_f32_e32 v125, v139
	v_cvt_pk_bf16_f32 v136, v163, v164
	v_cvt_pk_bf16_f32 v137, v165, v162
	v_cvt_pk_bf16_f32 v138, v118, v116
	v_cvt_pk_bf16_f32 v139, v117, v98
	v_exp_f32_e32 v174, v86
	v_add_u32_e32 v86, 0x1b0c0, v185
	s_waitcnt lgkmcnt(4)
	v_mfma_f32_32x32x16_bf16 v[50:65], v[132:135], v[136:139], v[50:65]
	v_exp_f32_e32 v175, v87
	v_add_u32_e32 v87, 0x1bac0, v185
	ds_read_b64_tr_b16 v[132:133], v86
	ds_read_b64_tr_b16 v[134:135], v87
	v_exp_f32_e32 v176, v88
	v_exp_f32_e32 v177, v89
	v_cvt_pk_bf16_f32 v86, v114, v115
	v_cvt_pk_bf16_f32 v87, v122, v123
	s_waitcnt lgkmcnt(2)
	v_mfma_f32_32x32x16_bf16 v[34:49], v[82:85], v[136:139], v[34:49]
	v_add_u32_e32 v82, 0x1c400, v185
	v_add_u32_e32 v84, 0x1ce00, v185
	ds_read_b64_tr_b16 v[82:83], v82
	ds_read_b64_tr_b16 v[84:85], v84
	v_cvt_pk_bf16_f32 v88, v119, v120
	v_cvt_pk_bf16_f32 v89, v121, v124
	v_exp_f32_e32 v192, v90
	v_add_u32_e32 v90, 0x1c440, v185
	v_mfma_f32_32x32x16_bf16 v[66:81], v[140:143], v[136:139], v[66:81]
	v_exp_f32_e32 v193, v91
	v_exp_f32_e32 v91, v93
	v_exp_f32_e32 v93, v95
	v_add_u32_e32 v95, 0x1c4c0, v185
	v_exp_f32_e32 v111, v144
	v_add_u32_e32 v144, 0x1ec40, v185
	v_exp_f32_e32 v112, v145
	s_waitcnt lgkmcnt(2)
	v_mfma_f32_32x32x16_bf16 v[18:33], v[132:135], v[136:139], v[18:33]
	v_add_u32_e32 v134, 0x1ce40, v185
	ds_read_b64_tr_b16 v[132:133], v90
	ds_read_b64_tr_b16 v[134:135], v134
	v_exp_f32_e32 v90, v92
	v_exp_f32_e32 v92, v94
	v_exp_f32_e32 v94, v96
	v_add_u32_e32 v96, 0x1cec0, v185
	v_cvt_pk_bf16_f32 v136, v166, v168
	s_waitcnt lgkmcnt(2)
	v_mfma_f32_32x32x16_bf16 v[50:65], v[82:85], v[86:89], v[50:65]
	v_add_u32_e32 v82, 0x1c480, v185
	v_add_u32_e32 v84, 0x1ce80, v185
	ds_read_b64_tr_b16 v[82:83], v82
	ds_read_b64_tr_b16 v[84:85], v84
	v_cvt_pk_bf16_f32 v137, v169, v173
	v_cvt_pk_bf16_f32 v138, v160, v159
	v_cvt_pk_bf16_f32 v139, v170, v171
	s_waitcnt lgkmcnt(0)
	v_mfma_f32_32x32x16_bf16 v[34:49], v[82:85], v[86:89], v[34:49]
	v_add_u32_e32 v82, 0x1d800, v185
	v_add_u32_e32 v84, 0x1e200, v185
	v_mfma_f32_32x32x16_bf16 v[66:81], v[132:135], v[86:89], v[66:81]
	ds_read_b64_tr_b16 v[132:133], v95
	ds_read_b64_tr_b16 v[134:135], v96
	ds_read_b64_tr_b16 v[82:83], v82
	ds_read_b64_tr_b16 v[84:85], v84
	v_add_u32_e32 v96, 0x1d880, v185
	v_exp_f32_e32 v95, v97
	v_add_u32_e32 v97, 0x1d8c0, v185
	s_waitcnt lgkmcnt(2)
	v_mfma_f32_32x32x16_bf16 v[18:33], v[132:135], v[86:89], v[18:33]
	v_add_u32_e32 v86, 0x1d840, v185
	v_add_u32_e32 v88, 0x1e240, v185
	v_add_u32_e32 v134, 0x1e2c0, v185
	ds_read_b64_tr_b16 v[86:87], v86
	ds_read_b64_tr_b16 v[88:89], v88
	s_waitcnt lgkmcnt(2)
	v_mfma_f32_32x32x16_bf16 v[50:65], v[82:85], v[136:139], v[50:65]
	v_add_u32_e32 v84, 0x1e280, v185
	ds_read_b64_tr_b16 v[82:83], v96
	ds_read_b64_tr_b16 v[84:85], v84
	ds_read_b64_tr_b16 v[132:133], v97
	ds_read_b64_tr_b16 v[134:135], v134
	v_add_u32_e32 v96, 0x1ec00, v185
	v_add_u32_e32 v97, 0x1f600, v185
	ds_read_b64_tr_b16 v[140:141], v96
	ds_read_b64_tr_b16 v[142:143], v97
	ds_read_b64_tr_b16 v[144:145], v144
	v_add_f32_e32 v96, 0, v166
	v_add_f32_e32 v96, v168, v96
	v_add_f32_e32 v96, v169, v96
	v_add_f32_e32 v96, v173, v96
	s_waitcnt lgkmcnt(5)
	v_mfma_f32_32x32x16_bf16 v[34:49], v[82:85], v[136:139], v[34:49]
	v_add_u32_e32 v82, 0x1f640, v185
	v_add_f32_e32 v97, v160, v96
	ds_read_b64_tr_b16 v[146:147], v82
	v_add_u32_e32 v82, 0x1ec80, v185
	v_add_f32_e32 v97, v159, v97
	ds_read_b64_tr_b16 v[148:149], v82
	v_add_u32_e32 v82, 0x1f680, v185
	v_add_f32_e32 v97, v170, v97
	ds_read_b64_tr_b16 v[150:151], v82
	v_add_u32_e32 v82, 0x1ecc0, v185
	v_add_f32_e32 v97, v171, v97
	v_mfma_f32_32x32x16_bf16 v[66:81], v[86:89], v[136:139], v[66:81]
	v_cvt_pk_bf16_f32 v86, v172, v129
	v_cvt_pk_bf16_f32 v87, v158, v167
	v_cvt_pk_bf16_f32 v88, v161, v127
	v_cvt_pk_bf16_f32 v89, v128, v126
	ds_read_b64_tr_b16 v[152:153], v82
	v_add_u32_e32 v82, 0x1f6c0, v185
	v_add_f32_e32 v97, v172, v97
	ds_read_b64_tr_b16 v[154:155], v82
	s_waitcnt lgkmcnt(6)
	v_mfma_f32_32x32x16_bf16 v[50:65], v[140:143], v[86:89], v[50:65]
	v_add_u32_e32 v140, 0x20000, v185
	v_add_u32_e32 v142, 0x20a00, v185
	v_add_f32_e32 v97, v129, v97
	ds_read_b64_tr_b16 v[140:141], v140
	ds_read_b64_tr_b16 v[142:143], v142
	v_add_f32_e32 v97, v158, v97
	v_add_f32_e32 v97, v167, v97
	v_mfma_f32_32x32x16_bf16 v[18:33], v[132:135], v[136:139], v[18:33]
	v_add_f32_e32 v97, v161, v97
	v_add_f32_e32 v97, v127, v97
	v_add_f32_e32 v97, v128, v97
	v_add_f32_e32 v97, v126, v97
	v_cvt_pk_bf16_f32 v136, v130, v131
	v_add_u32_e32 v129, 0x200c0, v185
	v_add_f32_e32 v97, v130, v97
	v_add_f32_e32 v130, 0, v163
	s_waitcnt lgkmcnt(4)
	v_mfma_f32_32x32x16_bf16 v[34:49], v[148:151], v[86:89], v[34:49]
	ds_read_b64_tr_b16 v[148:149], v129
	v_add_u32_e32 v129, 0x20ac0, v185
	v_add_u32_e32 v126, 0x21400, v185
	v_add_u32_e32 v128, 0x21e00, v185
	v_add_f32_e32 v130, v164, v130
	v_cvt_pk_bf16_f32 v82, v99, v100
	v_cvt_pk_bf16_f32 v83, v113, v101
	v_cvt_pk_bf16_f32 v84, v102, v103
	v_cvt_pk_bf16_f32 v85, v104, v105
	v_mfma_f32_32x32x16_bf16 v[66:81], v[144:147], v[86:89], v[66:81]
	ds_read_b64_tr_b16 v[150:151], v129
	ds_read_b64_tr_b16 v[126:127], v126
	ds_read_b64_tr_b16 v[128:129], v128
	v_add_f32_e32 v130, v165, v130
	v_add_f32_e32 v130, v162, v130
	v_add_f32_e32 v118, v118, v130
	v_add_f32_e32 v116, v116, v118
	s_waitcnt lgkmcnt(6)
	v_mfma_f32_32x32x16_bf16 v[18:33], v[152:155], v[86:89], v[18:33]
	v_add_u32_e32 v86, 0x20080, v185
	v_add_u32_e32 v88, 0x20a80, v185
	ds_read_b64_tr_b16 v[86:87], v86
	ds_read_b64_tr_b16 v[88:89], v88
	v_add_u32_e32 v144, 0x20040, v185
	v_add_u32_e32 v146, 0x20a40, v185
	v_add_f32_e32 v116, v117, v116
	s_waitcnt lgkmcnt(6)
	v_mfma_f32_32x32x16_bf16 v[50:65], v[140:143], v[82:85], v[50:65]
	ds_read_b64_tr_b16 v[144:145], v144
	ds_read_b64_tr_b16 v[146:147], v146
	v_add_f32_e32 v98, v98, v116
	v_add_f32_e32 v98, v114, v98
	v_add_f32_e32 v98, v115, v98
	v_cvt_pk_bf16_f32 v132, v106, v125
	v_cvt_pk_bf16_f32 v133, v107, v108
	v_cvt_pk_bf16_f32 v134, v109, v110
	v_cvt_pk_bf16_f32 v135, v111, v112
	v_add_f32_e32 v98, v122, v98
	v_add_f32_e32 v98, v123, v98
	s_waitcnt lgkmcnt(4)
	v_mfma_f32_32x32x16_bf16 v[50:65], v[126:129], v[132:135], v[50:65]
	v_add_f32_e32 v98, v119, v98
	v_add_f32_e32 v98, v120, v98
	v_add_f32_e32 v97, v131, v97
	v_add_f32_e32 v98, v121, v98
	v_add_u32_e32 v140, 0x21440, v185
	v_add_u32_e32 v142, 0x21e40, v185
	v_add_f32_e32 v97, v156, v97
	s_waitcnt lgkmcnt(2)
	v_mfma_f32_32x32x16_bf16 v[34:49], v[86:89], v[82:85], v[34:49]
	v_add_f32_e32 v98, v124, v98
	v_cvt_pk_bf16_f32 v137, v156, v157
	ds_read_b64_tr_b16 v[140:141], v140
	ds_read_b64_tr_b16 v[142:143], v142
	v_add_f32_e32 v97, v157, v97
	v_add_f32_e32 v98, v99, v98
	v_add_f32_e32 v98, v100, v98
	s_waitcnt lgkmcnt(2)
	v_mfma_f32_32x32x16_bf16 v[66:81], v[144:147], v[82:85], v[66:81]
	ds_read_b64_tr_b16 v[144:145], v238
	ds_read_b64_tr_b16 v[146:147], v239
	ds_read_b64_tr_b16 v[152:153], v240
	ds_read_b64_tr_b16 v[154:155], v241
	ds_read_b64_tr_b16 v[86:87], v242
	ds_read_b64_tr_b16 v[88:89], v243
	ds_read_b64_tr_b16 v[156:157], v244
	ds_read_b64_tr_b16 v[158:159], v245
	v_cvt_pk_bf16_f32 v138, v174, v175
	v_cvt_pk_bf16_f32 v139, v176, v177
	v_add_f32_e32 v98, v113, v98
	v_add_f32_e32 v97, v174, v97
	v_add_f32_e32 v97, v175, v97
	s_waitcnt lgkmcnt(2)
	v_mfma_f32_32x32x16_bf16 v[50:65], v[86:89], v[136:139], v[50:65]
	v_add_f32_e32 v86, v101, v98
	v_add_f32_e32 v86, v102, v86
	v_add_f32_e32 v86, v103, v86
	v_add_f32_e32 v97, v176, v97
	v_add_f32_e32 v86, v104, v86
	v_add_f32_e32 v97, v177, v97
	v_add_f32_e32 v86, v105, v86
	v_mfma_f32_32x32x16_bf16 v[34:49], v[144:147], v[132:135], v[34:49]
	v_add_f32_e32 v97, v192, v97
	v_add_f32_e32 v86, v106, v86
	v_add_f32_e32 v97, v193, v97
	v_add_f32_e32 v86, v125, v86
	v_add_f32_e32 v97, v90, v97
	v_add_f32_e32 v86, v107, v86
	v_add_f32_e32 v97, v91, v97
	v_mfma_f32_32x32x16_bf16 v[18:33], v[148:151], v[82:85], v[18:33]
	ds_read_b64_tr_b16 v[82:83], v246
	ds_read_b64_tr_b16 v[84:85], v247
	ds_read_b64_tr_b16 v[148:149], v248
	ds_read_b64_tr_b16 v[150:151], v249
	v_add_f32_e32 v86, v108, v86
	v_add_f32_e32 v97, v92, v97
	v_add_f32_e32 v86, v109, v86
	ds_read_b64_tr_b16 v[126:127], v250
	ds_read_b64_tr_b16 v[128:129], v251
	ds_read_b64_tr_b16 v[164:165], v252
	ds_read_b64_tr_b16 v[166:167], v253
	v_add_f32_e32 v97, v93, v97
	v_add_f32_e32 v86, v110, v86
	s_waitcnt lgkmcnt(6)
	v_mfma_f32_32x32x16_bf16 v[34:49], v[82:85], v[136:139], v[34:49]
	v_mov_b32_e32 v83, v179
	v_add_f32_e32 v97, v94, v97
	v_add_f32_e32 v86, v111, v86
	v_add_f32_e32 v97, v95, v97
	v_add_f32_e32 v86, v112, v86
	v_add_f32_e32 v86, v86, v97
	v_add_f32_e32 v82, v191, v86
	v_mfma_f32_32x32x16_bf16 v[66:81], v[140:143], v[132:135], v[66:81]
	ds_read_b64_tr_b16 v[140:141], v254
	ds_read_b64_tr_b16 v[142:143], v187
	ds_read_b64_tr_b16 v[160:161], v222
	ds_read_b64_tr_b16 v[162:163], v223
	s_waitcnt lgkmcnt(0)
	s_barrier
	v_cvt_pk_bf16_f32 v96, v192, v193
	v_mbcnt_lo_u32_b32 v83, -1, v83
	v_mfma_f32_32x32x16_bf16 v[18:33], v[152:155], v[132:135], v[18:33]
	v_mbcnt_hi_u32_b32 v87, -1, v83
	v_lshlrev_b32_e32 v83, 2, v87
	v_xor_b32_e32 v85, 0x80, v83
	ds_bpermute_b32 v83, v85, v82
	v_cvt_pk_bf16_f32 v97, v90, v91
	v_cvt_pk_bf16_f32 v98, v92, v93
	v_cvt_pk_bf16_f32 v99, v94, v95
	v_mfma_f32_32x32x16_bf16 v[66:81], v[156:159], v[136:139], v[66:81]
	s_waitcnt lgkmcnt(0)
	v_add_f32_e32 v82, v82, v83
	v_div_scale_f32 v83, s[44:45], v82, v82, 1.0
	v_rcp_f32_e32 v84, v83
	s_nop 0
	v_fma_f32 v86, -v83, v84, 1.0
	v_mfma_f32_32x32x16_bf16 v[18:33], v[148:151], v[136:139], v[18:33]
	v_fmac_f32_e32 v84, v86, v84
	v_div_scale_f32 v86, vcc, 1.0, v82, 1.0
	v_mul_f32_e32 v88, v86, v84
	v_fma_f32 v89, -v83, v88, v86
	v_fmac_f32_e32 v88, v89, v84
	v_fma_f32 v83, -v83, v88, v86
	v_mfma_f32_32x32x16_bf16 v[50:65], v[126:129], v[96:99], v[50:65]
	v_div_fmas_f32 v83, v83, v84, v88
	v_and_b32_e32 v86, 31, v87
	v_ashrrev_i32_e32 v87, 5, v87
	v_div_fixup_f32 v83, v83, v82, 1.0
	v_lshlrev_b32_e32 v82, 9, v87
	v_lshlrev_b32_e32 v88, 2, v86
	v_mul_f32_e32 v84, v224, v83
	v_mfma_f32_32x32x16_bf16 v[66:81], v[164:167], v[96:99], v[66:81]
	s_and_b64 vcc, exec, s[6:7]
	v_add3_u32 v82, s28, v82, v88
	v_mfma_f32_32x32x16_bf16 v[34:49], v[140:143], v[96:99], v[34:49]
	v_mfma_f32_32x32x16_bf16 v[18:33], v[160:163], v[96:99], v[18:33]
	s_cbranch_vccnz .LBB0_658
	v_mul_f32_e32 v88, v50, v84
	v_mul_f32_e32 v89, v51, v84
	ds_write2_b32 v82, v88, v89 offset1:32
	v_mul_f32_e32 v88, v52, v84
	v_mul_f32_e32 v89, v53, v84
	ds_write2_b32 v82, v88, v89 offset0:64 offset1:96
	v_mul_f32_e32 v88, v54, v84
	v_mul_f32_e32 v89, v55, v84
	v_add_u32_e32 v90, 0x400, v82
	ds_write2_b32 v90, v88, v89 offset1:32
	v_mul_f32_e32 v88, v56, v84
	v_mul_f32_e32 v89, v57, v84
	ds_write2_b32 v90, v88, v89 offset0:64 offset1:96
	v_mul_f32_e32 v88, v58, v84
	v_mul_f32_e32 v89, v59, v84
	v_add_u32_e32 v90, 0x800, v82
	ds_write2_b32 v90, v88, v89 offset1:32
	v_mul_f32_e32 v88, v60, v84
	v_mul_f32_e32 v89, v61, v84
	ds_write2_b32 v90, v88, v89 offset0:64 offset1:96
	v_mul_f32_e32 v88, v62, v84
	v_mul_f32_e32 v89, v63, v84
	v_add_u32_e32 v90, 0xc00, v82
	ds_write2_b32 v90, v88, v89 offset1:32
	v_mul_f32_e32 v88, v64, v84
	v_mul_f32_e32 v89, v65, v84
	ds_write2_b32 v90, v88, v89 offset0:64 offset1:96
	v_mul_f32_e32 v88, v66, v84
	v_mul_f32_e32 v89, v67, v84
	v_add_u32_e32 v90, 0x1000, v82
	ds_write2_b32 v90, v88, v89 offset1:32
	v_mul_f32_e32 v88, v68, v84
	v_mul_f32_e32 v89, v69, v84
	ds_write2_b32 v90, v88, v89 offset0:64 offset1:96
	v_mul_f32_e32 v88, v70, v84
	v_mul_f32_e32 v89, v71, v84
	v_add_u32_e32 v90, 0x1400, v82
	ds_write2_b32 v90, v88, v89 offset1:32
	v_mul_f32_e32 v88, v72, v84
	v_mul_f32_e32 v89, v73, v84
	ds_write2_b32 v90, v88, v89 offset0:64 offset1:96
	v_mul_f32_e32 v88, v74, v84
	v_mul_f32_e32 v89, v75, v84
	v_add_u32_e32 v90, 0x1800, v82
	ds_write2_b32 v90, v88, v89 offset1:32
	v_mul_f32_e32 v88, v76, v84
	v_mul_f32_e32 v89, v77, v84
	ds_write2_b32 v90, v88, v89 offset0:64 offset1:96
	v_mul_f32_e32 v88, v78, v84
	v_mul_f32_e32 v89, v79, v84
	v_add_u32_e32 v90, 0x1c00, v82
	ds_write2_b32 v90, v88, v89 offset1:32
	v_mul_f32_e32 v88, v80, v84
	v_mul_f32_e32 v89, v81, v84
	ds_write2_b32 v90, v88, v89 offset0:64 offset1:96
	v_mul_f32_e32 v88, v34, v84
	v_mul_f32_e32 v89, v35, v84
	v_add_u32_e32 v90, 0x2000, v82
	ds_write2_b32 v90, v88, v89 offset1:32
	v_mul_f32_e32 v88, v36, v84
	v_mul_f32_e32 v89, v37, v84
	ds_write2_b32 v90, v88, v89 offset0:64 offset1:96
	v_mul_f32_e32 v88, v38, v84
	v_mul_f32_e32 v89, v39, v84
	v_add_u32_e32 v90, 0x2400, v82
	ds_write2_b32 v90, v88, v89 offset1:32
	v_mul_f32_e32 v88, v40, v84
	v_mul_f32_e32 v89, v41, v84
	ds_write2_b32 v90, v88, v89 offset0:64 offset1:96
	v_mul_f32_e32 v88, v42, v84
	v_mul_f32_e32 v89, v43, v84
	v_add_u32_e32 v90, 0x2800, v82
	ds_write2_b32 v90, v88, v89 offset1:32
	v_mul_f32_e32 v88, v44, v84
	v_mul_f32_e32 v89, v45, v84
	ds_write2_b32 v90, v88, v89 offset0:64 offset1:96
	v_mul_f32_e32 v88, v46, v84
	v_mul_f32_e32 v89, v47, v84
	v_add_u32_e32 v90, 0x2c00, v82
	ds_write2_b32 v90, v88, v89 offset1:32
	v_mul_f32_e32 v88, v48, v84
	v_mul_f32_e32 v89, v49, v84
	ds_write2_b32 v90, v88, v89 offset0:64 offset1:96
	v_mul_f32_e32 v88, v18, v84
	v_mul_f32_e32 v89, v19, v84
	v_add_u32_e32 v90, 0x3000, v82
	ds_write2_b32 v90, v88, v89 offset1:32
	v_mul_f32_e32 v88, v20, v84
	v_mul_f32_e32 v89, v21, v84
	ds_write2_b32 v90, v88, v89 offset0:64 offset1:96
	v_mul_f32_e32 v88, v22, v84
	v_mul_f32_e32 v89, v23, v84
	v_add_u32_e32 v90, 0x3400, v82
	ds_write2_b32 v90, v88, v89 offset1:32
	v_mul_f32_e32 v88, v24, v84
	v_mul_f32_e32 v89, v25, v84
	ds_write2_b32 v90, v88, v89 offset0:64 offset1:96
	v_mul_f32_e32 v88, v26, v84
	v_mul_f32_e32 v89, v27, v84
	v_add_u32_e32 v90, 0x3800, v82
	ds_write2_b32 v90, v88, v89 offset1:32
	v_mul_f32_e32 v88, v28, v84
	v_mul_f32_e32 v89, v29, v84
	ds_write2_b32 v90, v88, v89 offset0:64 offset1:96
	v_mul_f32_e32 v88, v30, v84
	v_mul_f32_e32 v89, v31, v84
	v_add_u32_e32 v90, 0x3c00, v82
	ds_write2_b32 v90, v88, v89 offset1:32
	v_mul_f32_e32 v88, v32, v84
	v_mul_f32_e32 v89, v33, v84
	ds_write2_b32 v90, v88, v89 offset0:64 offset1:96

	.amdhsa_kernel _Z10hybrid_fwd4Args
		.amdhsa_group_segment_fixed_size 0
		.amdhsa_private_segment_fixed_size 0
		.amdhsa_kernarg_size 528
		.amdhsa_user_sgpr_count 2
		.amdhsa_user_sgpr_dispatch_ptr 0
		.amdhsa_user_sgpr_queue_ptr 0
		.amdhsa_user_sgpr_kernarg_segment_ptr 1
		.amdhsa_user_sgpr_dispatch_id 0
		.amdhsa_user_sgpr_kernarg_preload_length 0
		.amdhsa_user_sgpr_kernarg_preload_offset 0
		.amdhsa_user_sgpr_private_segment_size 0
		.amdhsa_uses_dynamic_stack 0
		.amdhsa_enable_private_segment 0
		.amdhsa_system_sgpr_workgroup_id_x 1
		.amdhsa_system_sgpr_workgroup_id_y 0
		.amdhsa_system_sgpr_workgroup_id_z 0
		.amdhsa_system_sgpr_workgroup_info 0
		.amdhsa_system_vgpr_workitem_id 2
		.amdhsa_next_free_vgpr 256
		.amdhsa_next_free_sgpr 100
		.amdhsa_accum_offset 256
		.amdhsa_reserve_vcc 1
		.amdhsa_float_round_mode_32 0
		.amdhsa_float_round_mode_16_64 0
		.amdhsa_float_denorm_mode_32 3
		.amdhsa_float_denorm_mode_16_64 3
		.amdhsa_dx10_clamp 1
		.amdhsa_ieee_mode 1
		.amdhsa_fp16_overflow 0
		.amdhsa_tg_split 0
		.amdhsa_exception_fp_ieee_invalid_op 0
		.amdhsa_exception_fp_denorm_src 0
		.amdhsa_exception_fp_ieee_div_zero 0
		.amdhsa_exception_fp_ieee_overflow 0
		.amdhsa_exception_fp_ieee_underflow 0
		.amdhsa_exception_fp_ieee_inexact 0
		.amdhsa_exception_int_div_zero 0
	.end_amdhsa_kernel

amdhsa.kernels:
  - .agpr_count:     0
    .args:
      - .offset:         0
        .size:           272
        .value_kind:     by_value
      - .offset:         272
        .size:           4
        .value_kind:     hidden_block_count_x
      - .offset:         276
        .size:           4
        .value_kind:     hidden_block_count_y
      - .offset:         280
        .size:           4
        .value_kind:     hidden_block_count_z
      - .offset:         284
        .size:           2
        .value_kind:     hidden_group_size_x
      - .offset:         286
        .size:           2
        .value_kind:     hidden_group_size_y
      - .offset:         288
        .size:           2
        .value_kind:     hidden_group_size_z
      - .offset:         290
        .size:           2
        .value_kind:     hidden_remainder_x
      - .offset:         292
        .size:           2
        .value_kind:     hidden_remainder_y
      - .offset:         294
        .size:           2
        .value_kind:     hidden_remainder_z
      - .offset:         312
        .size:           8
        .value_kind:     hidden_global_offset_x
      - .offset:         320
        .size:           8
        .value_kind:     hidden_global_offset_y
      - .offset:         328
        .size:           8
        .value_kind:     hidden_global_offset_z
      - .offset:         336
        .size:           2
        .value_kind:     hidden_grid_dims
      - .offset:         360
        .size:           8
        .value_kind:     hidden_multigrid_sync_arg
      - .offset:         392
        .size:           4
        .value_kind:     hidden_dynamic_lds_size
    .group_segment_fixed_size: 0
    .kernarg_segment_align: 8
    .kernarg_segment_size: 528
    .language:       OpenCL C
    .language_version:
      - 2
      - 0
    .max_flat_workgroup_size: 512
    .name:           _Z10hybrid_fwd4Args
    .private_segment_fixed_size: 0
    .sgpr_count:     106
    .sgpr_spill_count: 15
    .symbol:         _Z10hybrid_fwd4Args.kd
    .uniform_work_group_size: 1
    .uses_dynamic_stack: false
    .vgpr_count:     256
    .vgpr_spill_count: 0
    .wavefront_size: 64
